# weight conversion tile ranges re-split: phase0 2496 tiles, in_proj tail 2016, gate-up tail 1024, kvq tail 1280 (each weight still converted before first use)
# speedup vs baseline: 1.0430x; 1.0033x over previous
.LBB0_935:
	v_readlane_b32 s0, v254, 0
	s_load_dword s50, s[74:75], 0x0
	v_readlane_b32 s6, v255, 30
	s_mov_b32 s30, s6
	v_readlane_b32 s7, v255, 31
	s_waitcnt lgkmcnt(0)
	s_cmpk_eq_i32 s50, 0x100
	s_cselect_b64 s[4:5], -1, 0
	s_cmp_lg_u32 s6, 0
	s_cbranch_scc0 .LBB0_987
	s_cmp_eq_u32 s30, 1
	s_cselect_b64 s[6:7], -1, 0
	s_cmp_gt_i32 s0, 31
	s_cselect_b64 s[8:9], -1, 0
	s_and_b64 s[6:7], s[6:7], s[8:9]
	s_and_b64 s[6:7], s[6:7], s[4:5]
	s_andn2_b64 vcc, exec, s[6:7]
	s_mov_b64 s[6:7], -1
	s_cbranch_vccz .LBB0_943
	s_cmp_eq_u32 s30, 8
	s_cselect_b64 s[6:7], -1, 0
	s_and_b64 s[6:7], s[6:7], s[4:5]
	s_cmpk_gt_i32 s0, 0x7f
	s_cselect_b64 s[8:9], -1, 0
	s_and_b64 s[6:7], s[8:9], s[6:7]
	s_andn2_b64 vcc, exec, s[6:7]
	s_mov_b64 s[6:7], -1
	s_cbranch_vccz .LBB0_940
	s_cmp_eq_u32 s30, 11
	s_cselect_b64 s[6:7], -1, 0
	s_and_b64 s[6:7], s[6:7], s[4:5]
	s_and_b64 s[6:7], s[8:9], s[6:7]
	s_andn2_b64 vcc, exec, s[6:7]
	s_mov_b32 s10, 1
	s_cbranch_vccnz .LBB0_989
	s_add_i32 s17, s0, 0x1520
	s_movk_i32 s10, 0x80
	s_movk_i32 s11, 0x1aa0
	s_mov_b64 s[6:7], 0

.LBB0_941:
	s_add_i32 s17, s0, 0x1120
	s_movk_i32 s10, 0x80
	s_movk_i32 s11, 0x15a0

.LBB0_943:
	s_andn2_b64 vcc, exec, s[6:7]
	s_cbranch_vccnz .LBB0_945
	s_add_i32 s17, s0, 0x9a0
	s_movk_i32 s10, 0xe0
	s_movk_i32 s11, 0x11a0

.LBB0_946:
	s_and_b64 s[4:5], s[4:5], exec
	s_movk_i32 s1, 0x9c0
	s_cselect_b32 s11, s1, 0x1aa0
	s_mov_b32 s17, s0
	s_mov_b32 s10, s50
